# v13: + one static s_setprio 1 for waves 0-3 during the attention phase
# speedup vs baseline: 1.0233x; 1.0033x over previous
; __device__ __forceinline__ void phase_attn(const bf16_t* QH, const bf16_t* KNH, const bf16_t* VH, const bf16_t* KRO, bf16_t* Z, int half, char* lds, int wv, bool nowrite) {
;     const int c = blockIdx.x, G = gridDim.x;
;     const int per = 2048 / G;
;     for (int i = 0; i < per; ++i) {
;         int bh, qb;
;         if (G == 256) { const int xcd = c & 7, slot = c >> 3; bh = i * 32 + xcd * 4 + (slot >> 3); qb = slot & 7; }
;         else { const int u = i * G + c; bh = u >> 3; qb = u & 7; }
;         const int bl = bh >> 4, h = bh & 15;
;         const size_t lrow = (size_t)bl * SEQ, grow = (size_t)half * TH + lrow;
.LBB0_599:
	s_and_b64 vcc, exec, s[12:13]
	s_cbranch_vccz .LBB0_625
	v_readlane_b32 s2, v254, 2
	s_nop 1
	s_lshr_b32 s2, s2, 6
	s_cmp_lt_u32 s2, 4
	s_cbranch_scc0 .Latt_prio_done
	s_setprio 1
.Latt_prio_done:
	s_abs_i32 s2, s79
	v_cvt_f32_u32_e32 v0, s2
	s_sub_i32 s6, 0, s2
	s_ashr_i32 s3, s79, 31
	v_rcp_iflag_f32_e32 v0, v0
	s_nop 0
	v_mul_f32_e32 v0, 0x4f7ffffe, v0
	v_cvt_u32_f32_e32 v0, v0
	s_nop 0
	v_readfirstlane_b32 s7, v0
	s_mul_i32 s6, s6, s7
	s_mul_hi_u32 s6, s7, s6
	s_add_i32 s7, s7, s6
	s_lshr_b32 s6, s7, 21
	s_mul_i32 s7, s6, s2
	s_sub_i32 s7, 0x800, s7
	s_add_i32 s8, s6, 1
	s_sub_i32 s9, s7, s2
	s_cmp_ge_u32 s7, s2
	s_cselect_b32 s6, s8, s6
	s_cselect_b32 s7, s9, s7
	s_add_i32 s8, s6, 1
	s_cmp_ge_u32 s7, s2
	s_cselect_b32 s2, s8, s6
	s_xor_b32 s2, s2, s3
	s_sub_i32 s34, s2, s3
	s_cmp_gt_i32 s34, 0
	s_cbranch_scc0 .LBB0_624
	s_add_u32 s35, s44, 0x1c000000
	s_addc_u32 s50, s45, 0
	s_add_u32 s51, s44, 0x28000000
	s_addc_u32 s64, s45, 0
	s_add_u32 s65, s44, 0x30000000
	s_addc_u32 s70, s45, 0
	s_add_u32 s71, s44, 0x3e000000
	s_addc_u32 s76, s45, 0
	s_add_u32 s77, s44, 0xc000000
	s_addc_u32 s78, s45, 0
	v_readlane_b32 s2, v255, 14
	s_cmpk_lg_i32 s2, 0x100
	s_cselect_b64 s[58:59], -1, 0
	s_lshl_b32 s68, s20, 15
	s_mov_b32 s69, s25
	s_mov_b32 s79, 0
	s_lshl_b64 s[72:73], s[68:69], 7
	s_branch .LBB0_603

; __device__ __forceinline__ void phase_attn(const bf16_t* QH, const bf16_t* KNH, const bf16_t* VH, const bf16_t* KRO, bf16_t* Z, int half, char* lds, int wv, bool nowrite) {
;     const int c = blockIdx.x, G = gridDim.x;
;     const int per = 2048 / G;
;     for (int i = 0; i < per; ++i) {
;         int bh, qb;
;         if (G == 256) { const int xcd = c & 7, slot = c >> 3; bh = i * 32 + xcd * 4 + (slot >> 3); qb = slot & 7; }
;         else { const int u = i * G + c; bh = u >> 3; qb = u & 7; }
;         const int bl = bh >> 4, h = bh & 15;
;         const size_t lrow = (size_t)bl * SEQ, grow = (size_t)half * TH + lrow;
;         attn_body(QH + (lrow + qb * 256) * LDQ + h * 192, KNH + lrow * LDK + h * 128, VH + lrow * LDK + h * 128, KRO + grow * 64,
;                   Z + (grow + qb * 256) * LDZ + h * 128, SEQ, lds, wv, nowrite);
;     }
; }
.LBB0_624:
	s_setprio 0
	s_mov_b64 s[60:61], 0
	v_readlane_b32 s79, v255, 14
